# grid barrier P8->P9 replaced by a 64-producer counter; consumers wait only before the sample-row small GEMM of P9
# speedup vs baseline: 1.0095x; 1.0095x over previous
.LBB0_1169:
	s_waitcnt vmcnt(0)
	s_barrier
	s_mov_b64 s[0:1], exec
	v_readlane_b32 s4, v245, 16
	v_readlane_b32 s5, v245, 17
	s_and_b64 s[4:5], s[0:1], s[4:5]
	s_mov_b64 exec, s[4:5]
	s_cbranch_execz .LBB0_1221
	s_cmpk_gt_u32 s2, 0x3f
	s_cbranch_scc1 .Lb8p_done
	buffer_wbl2 sc1
	s_waitcnt vmcnt(0)
	s_add_u32 s4, s66, 0x8100
	s_addc_u32 s5, s67, 0
	v_mov_b32_e32 v0, 0
	v_mov_b32_e32 v1, 1
	global_atomic_add v0, v1, s[4:5]
.Lb8p_done:
.LBB0_1221:
	s_or_b64 exec, exec, s[0:1]
	s_mov_b64 s[4:5], s[66:67]
	s_mov_b64 s[0:1], s[64:65]
	v_mov_b32_e32 v13, v220
	s_waitcnt lgkmcnt(0)
	s_barrier
	s_and_b64 vcc, exec, s[42:43]
	v_readfirstlane_b32 s40, v13
	s_cbranch_vccz .LBB0_1241
	v_lshlrev_b32_e32 v0, 4, v13
	v_add_u32_e32 v1, 0x2000, v0
	v_ashrrev_i32_e32 v2, 31, v1
	v_lshrrev_b32_e32 v2, 22, v2
	v_add_u32_e32 v2, v1, v2
	v_ashrrev_i32_e32 v8, 10, v2
	v_mul_i32_i24_e32 v2, 0x400, v8
	v_sub_u32_e32 v1, v1, v2
	v_lshrrev_b32_e32 v2, 4, v1
	v_bitop3_b32 v1, v2, v1, 32 bitop3:0x6c
	v_ashrrev_i32_e32 v2, 31, v1
	v_lshrrev_b32_e32 v2, 26, v2
	v_add_u32_e32 v2, v1, v2
	v_lshlrev_b32_e32 v3, 3, v8
	v_ashrrev_i32_e32 v9, 6, v2
	v_and_b32_e32 v3, -16, v3
	v_add_u32_e32 v3, v9, v3
	v_and_b32_e32 v4, 3, v9
	s_mov_b32 s0, 0x1fffe0
	v_lshrrev_b32_e32 v5, 2, v3
	v_lshlrev_b32_e32 v6, 1, v3
	v_and_b32_e32 v2, 0xc0, v2
	v_and_or_b32 v4, v3, s0, v4
	v_and_b32_e32 v5, 4, v5
	v_and_b32_e32 v6, 24, v6
	v_sub_u32_e32 v1, v1, v2
	v_mov_b32_e32 v2, 1
	v_or3_b32 v4, v4, v5, v6
	v_lshlrev_b32_e32 v5, 5, v8
	v_ashrrev_i16_sdwa v1, v2, sext(v1) dst_sel:DWORD dst_unused:UNUSED_PAD src0_sel:DWORD src1_sel:BYTE_0
	v_and_b32_e32 v5, 32, v5
	v_bfe_i32 v10, v1, 0, 16
	v_add_lshl_u32 v1, v5, v10, 1
	v_lshl_add_u32 v128, v4, 11, v1
	v_lshl_add_u32 v130, v3, 11, v1
	v_bfe_i32 v1, v13, 27, 1
	v_lshrrev_b32_e32 v1, 22, v1
	v_add_u32_e32 v1, v0, v1
	v_and_b32_e32 v1, 0xfffffc00, v1
	v_sub_u32_e32 v0, v0, v1
	v_lshrrev_b32_e32 v1, 4, v0
	v_ashrrev_i32_e32 v3, 31, v13
	v_bitop3_b32 v0, v1, v0, 32 bitop3:0x6c
	v_lshrrev_b32_e32 v3, 26, v3
	v_ashrrev_i32_e32 v1, 31, v0
	v_add_u32_e32 v3, v13, v3
	v_lshrrev_b32_e32 v1, 26, v1
	v_ashrrev_i32_e32 v12, 6, v3
	s_add_u32 s15, s4, 0xb800000
	v_add_u32_e32 v1, v0, v1
	v_lshlrev_b32_e32 v3, 3, v12
	s_addc_u32 s20, s5, 0
	v_ashrrev_i32_e32 v11, 6, v1
	v_and_b32_e32 v3, -16, v3
	s_add_u32 s21, s4, 0x1f080000
	v_add_u32_e32 v3, v11, v3
	v_and_b32_e32 v4, 3, v11
	s_addc_u32 s22, s5, 0
	v_and_or_b32 v4, v3, s0, v4
	s_lshr_b32 s0, s3, 29
	s_add_i32 s0, s2, s0
	s_and_b32 s1, s0, -8
	s_ashr_i32 s10, s40, 6
	s_sub_i32 s1, s2, s1
	s_ashr_i32 s11, s40, 8
	s_lshl_b32 s23, s10, 10
	s_lshl_b32 s7, s1, 6
	s_ashr_i32 s0, s0, 3
	s_mul_i32 s6, s1, 0x41
	s_cmp_lt_i32 s1, 0
	s_cselect_b32 s1, s6, s7
	s_add_i32 s0, s1, s0
	s_ashr_i32 s1, s0, 31
	s_lshr_b32 s1, s1, 27
	s_add_i32 s1, s0, s1
	s_ashr_i32 s6, s1, 5
	s_andn2_b32 s1, s1, 31
	s_sub_i32 s0, s0, s1
	s_bfe_i32 s1, s0, 0x80000
	s_bfe_u32 s1, s1, 0x3000c
	s_add_i32 s1, s0, s1
	s_bfe_i32 s7, s1, 0x80000
	s_and_b32 s1, s1, 0xf8
	s_sub_i32 s0, s0, s1
	s_lshl_b32 s6, s6, 3
	s_sext_i32_i16 s7, s7
	s_sext_i32_i8 s0, s0
	s_add_i32 s48, s6, s0
	s_ashr_i32 s0, s7, 3
	s_cmp_gt_i32 s48, 63
	s_cselect_b32 s1, 4, 0
	v_lshrrev_b32_e32 v5, 2, v3
	v_lshlrev_b32_e32 v6, 1, v3
	v_and_b32_e32 v1, 0xc0, v1
	s_add_i32 s0, s1, s0
	v_and_b32_e32 v5, 4, v5
	v_and_b32_e32 v6, 24, v6
	v_sub_u32_e32 v0, v0, v1
	s_ashr_i32 s49, s48, 31
	s_ashr_i32 s1, s0, 31
	v_or3_b32 v4, v4, v5, v6
	v_lshlrev_b32_e32 v5, 5, v12
	v_ashrrev_i16_sdwa v0, v2, sext(v0) dst_sel:DWORD dst_unused:UNUSED_PAD src0_sel:DWORD src1_sel:BYTE_0
	s_lshl_b64 s[6:7], s[48:49], 19
	s_lshl_b64 s[8:9], s[0:1], 19
	v_and_b32_e32 v5, 32, v5
	v_bfe_i32 v14, v0, 0, 16
	s_add_u32 s60, s21, s8
	v_add_lshl_u32 v0, v5, v14, 1
	s_addc_u32 s61, s22, s9
	s_add_i32 s33, s23, 0
	v_lshl_add_u32 v132, v4, 11, v0
	s_add_i32 m0, s33, 0x10000
	v_lshl_add_u32 v134, v3, 11, v0
	global_load_lds_dwordx4 v132, s[60:61]
	s_add_i32 m0, s33, 0x12000
	s_add_u32 s8, s60, 0x40000
	global_load_lds_dwordx4 v128, s[60:61]
	s_addc_u32 s9, s61, 0
	s_add_i32 m0, s33, 0x14000
	v_mov_b32_e32 v133, 0
	global_load_lds_dwordx4 v132, s[8:9]
	s_add_i32 m0, s33, 0x16000
	s_add_u32 s58, s15, s6
	s_addc_u32 s59, s20, s7
	s_add_i32 s49, s33, 0x2000
	global_load_lds_dwordx4 v128, s[8:9]
	s_mov_b32 m0, s33
	s_add_u32 s6, s58, 0x40000
	global_load_lds_dwordx4 v134, s[58:59]
	s_mov_b32 m0, s49
	s_addc_u32 s7, s59, 0
	s_add_i32 s64, s33, 0x4000
	global_load_lds_dwordx4 v130, s[58:59]
	s_mov_b32 m0, s64
	s_add_i32 s65, s33, 0x6000
	global_load_lds_dwordx4 v134, s[6:7]
	s_mov_b32 m0, s65
	v_mov_b32_e32 v129, v133
	global_load_lds_dwordx4 v130, s[6:7]
	v_mov_b32_e32 v135, v133
	v_mov_b32_e32 v131, v133
	s_cmp_eq_u32 s11, 1
	s_mov_b32 s1, 0
	v_lshl_add_u64 v[6:7], s[60:61], 0, v[132:133]
	v_lshl_add_u64 v[4:5], s[60:61], 0, v[128:129]
	v_lshl_add_u64 v[0:1], s[58:59], 0, v[134:135]
	s_cselect_b64 s[6:7], -1, 0
	s_cmp_lg_u32 s11, 1
	v_lshl_add_u64 v[2:3], s[58:59], 0, v[130:131]
	s_cbranch_scc1 .LBB0_1224
	s_barrier

.LBB0_1241:
	v_cmp_eq_u32_e32 vcc, 0, v220
	s_and_saveexec_b64 s[6:7], vcc
	s_cbranch_execz .Lb8_skip
	s_add_u32 s98, s4, 0x8100
	s_addc_u32 s99, s5, 0
	v_mov_b32_e32 v2, 0
	s_mov_b32 s100, 0
.Lb8_spin:
	global_load_dword v3, v2, s[98:99] sc1
	s_waitcnt vmcnt(0)
	v_readfirstlane_b32 s101, v3
	s_nop 3
	s_cmpk_ge_u32 s101, 0x40
	s_cbranch_scc1 .Lb8_done
	s_sleep 1
	s_add_i32 s100, s100, 1
	s_cmp_lt_u32 s100, 0x100000
	s_cbranch_scc1 .Lb8_spin

.Lb8_skip:
	s_or_b64 exec, exec, s[6:7]
	s_barrier
	v_mov_b32_e32 v0, v220
	s_and_b64 vcc, exec, s[38:39]
	s_cbranch_vccnz .LBB0_1244
	v_ashrrev_i32_e32 v4, 6, v0
	s_movk_i32 s0, 0x1e00
	v_mul_lo_u32 v2, v4, s0
	s_add_i32 s0, 0, 0x10000
	v_add_u32_e32 v5, s0, v2
	v_lshlrev_b32_e32 v2, 7, v4
	v_ashrrev_i32_e32 v3, 31, v2
	v_lshlrev_b32_e32 v7, 4, v0
	v_and_b32_e32 v32, 48, v7
	v_mov_b32_e32 v33, 0
	v_lshl_add_u64 v[2:3], v[2:3], 1, s[4:5]
	v_lshl_add_u64 v[2:3], v[2:3], 0, v[32:33]
	s_mov_b64 s[6:7], 0xb700000
	v_lshl_add_u64 v[34:35], v[2:3], 0, s[6:7]
	s_mov_b64 s[6:7], 0x1000000
	v_lshrrev_b32_e32 v16, 5, v0
	v_and_b32_e32 v6, 31, v0
	v_lshl_add_u64 v[36:37], v[2:3], 0, s[6:7]
	v_lshrrev_b32_e32 v2, 1, v0
	v_lshrrev_b32_e32 v12, 6, v0
	v_and_b32_e32 v16, 24, v16
	v_add_u32_e32 v7, v5, v32
	v_and_b32_e32 v8, 16, v2
	v_lshrrev_b32_e32 v2, 3, v0
	v_lshlrev_b32_e32 v32, 1, v6
	v_and_or_b32 v12, v12, 3, v16
	v_add_u32_e32 v16, 0x200, v0
	v_and_b32_e32 v41, 4, v2
	v_lshl_add_u64 v[2:3], s[4:5], 0, v[32:33]
	s_mov_b64 s[4:5], 0xf800000
	v_lshrrev_b32_e32 v17, 6, v16
	v_ashrrev_i32_e32 v18, 10, v16
	v_lshlrev_b32_e32 v19, 2, v16
	v_lshrrev_b32_e32 v16, 5, v16
	v_and_b32_e32 v1, 63, v0
	v_bfe_u32 v40, v0, 2, 4
	s_movk_i32 s0, 0x50
	v_lshl_add_u64 v[38:39], v[2:3], 0, s[4:5]
	v_add_u32_e32 v2, 0x600, v0
	v_ashrrev_i32_e32 v13, 10, v0
	v_lshlrev_b32_e32 v14, 2, v0
	v_and_b32_e32 v16, 24, v16
	v_add_u32_e32 v0, 0x400, v0
	v_mad_u32_u24 v5, v6, s0, v5
	v_ashrrev_i32_e32 v3, 10, v2
	v_lshrrev_b32_e32 v6, 6, v2
	v_lshlrev_b32_e32 v9, 2, v2
	v_and_or_b32 v16, v17, 3, v16
	v_lshrrev_b32_e32 v17, 6, v0
	v_ashrrev_i32_e32 v21, 10, v0
	v_lshlrev_b32_e32 v22, 2, v0
	v_lshrrev_b32_e32 v0, 5, v0
	v_lshrrev_b32_e32 v2, 5, v2
	v_lshl_add_u32 v1, v1, 2, 0
	v_and_b32_e32 v0, 24, v0
	v_and_b32_e32 v2, 24, v2
	v_lshlrev_b32_e32 v4, 13, v4
	v_and_b32_e32 v9, 0xf00, v9
	v_lshl_add_u32 v10, v3, 12, v1
	v_mul_u32_u24_e32 v11, 0x50, v40
	v_and_b32_e32 v14, 0xf00, v14
	v_lshl_add_u32 v15, v13, 12, v1
	v_and_b32_e32 v19, 0xf00, v19
	v_lshl_add_u32 v20, v18, 12, v1
	v_and_b32_e32 v22, 0xf00, v22
	v_lshl_add_u32 v23, v21, 12, v1
	v_and_or_b32 v0, v17, 3, v0
	v_and_or_b32 v2, v6, 3, v2
	s_mov_b32 s1, 0
	v_lshl_or_b32 v42, v13, 5, v12
	v_lshl_or_b32 v43, v18, 5, v16
	v_lshl_or_b32 v44, v21, 5, v0
	v_lshl_or_b32 v45, v3, 5, v2
	s_lshl_b32 s4, s2, 5
	s_lshl_b32 s5, s2, 1
	s_lshl_b32 s6, s96, 1
	v_add_u32_e32 v46, v7, v11
	v_add_u32_e32 v47, v5, v8
	v_add_u32_e32 v48, v1, v4
	v_add_u32_e32 v49, v15, v14
	v_add_u32_e32 v50, v20, v19
	v_add_u32_e32 v51, v23, v22
	v_add_u32_e32 v52, v10, v9
	s_mov_b32 s7, s2
	s_mov_b32 s9, 0x10000
